# v82: v78 pooling prefetch + dead-code elimination of 77 leftover address-arithmetic VALU in the pooling run
# baseline (speedup 1.0000x reference)
.LBB0_612:
	s_ashr_i32 s1, s0, 31
	s_lshl_b64 s[10:11], s[0:1], 10
	s_add_u32 s10, s34, s10
	s_addc_u32 s11, s35, s11
	s_bfe_u32 s16, s0, 0x90004
	s_and_b32 s17, s0, 0xffffe000
	s_lshl_b32 s1, s16, 4
	s_mul_i32 s16, s16, 0x1a000
	s_mul_hi_i32 s18, s17, 0x1a00
	s_mulk_i32 s17, 0x1a00
	s_add_u32 s16, s16, s17
	s_addc_u32 s17, 0, s18
	s_add_u32 s16, s34, s16
	s_addc_u32 s17, s35, s17
	s_lshl_b32 s18, s8, 4
	s_and_b32 s20, s18, 0x1ff0
	v_sub_u32_e32 v0, s20, v200
	s_and_b32 s21, s18, 0xffffe000
	v_mad_i64_i32 v[144:145], vcc, s21, v207, v[170:171]
	v_mov_b32_e32 v141, s20
	v_mov_b32_e32 v143, 0
	v_add_u32_e32 v140, 0, v0
	v_cmp_gt_u32_e32 vcc, s37, v140
	s_nop 1
	v_cndmask_b32_e32 v140, v141, v140, vcc
	v_mul_i32_i24_e32 v142, 0xd00, v140
	v_lshl_add_u64 v[146:147], v[142:143], 1, v[144:145]
	global_load_dwordx4 v[76:79], v[146:147], off offset:1536
	v_add_u32_e32 v140, 1, v0
	v_cmp_gt_u32_e32 vcc, s37, v140
	s_nop 1
	v_cndmask_b32_e32 v140, v141, v140, vcc
	v_mul_i32_i24_e32 v142, 0xd00, v140
	v_lshl_add_u64 v[146:147], v[142:143], 1, v[144:145]
	global_load_dwordx4 v[80:83], v[146:147], off offset:1536
	v_add_u32_e32 v140, 2, v0
	v_cmp_gt_u32_e32 vcc, s37, v140
	s_and_b64 vcc, s[38:39], vcc
	s_nop 1
	v_cndmask_b32_e32 v140, v141, v140, vcc
	v_mul_i32_i24_e32 v142, 0xd00, v140
	v_lshl_add_u64 v[146:147], v[142:143], 1, v[144:145]
	global_load_dwordx4 v[84:87], v[146:147], off offset:1536
	v_add_u32_e32 v140, 3, v0
	v_cmp_gt_u32_e32 vcc, s37, v140
	s_and_b64 vcc, s[38:39], vcc
	s_nop 1
	v_cndmask_b32_e32 v140, v141, v140, vcc
	v_mul_i32_i24_e32 v142, 0xd00, v140
	v_lshl_add_u64 v[146:147], v[142:143], 1, v[144:145]
	global_load_dwordx4 v[88:91], v[146:147], off offset:1536
	v_add_u32_e32 v140, 4, v0
	v_cmp_gt_u32_e32 vcc, s37, v140
	s_and_b64 vcc, s[40:41], vcc
	s_nop 1
	v_cndmask_b32_e32 v140, v141, v140, vcc
	v_mul_i32_i24_e32 v142, 0xd00, v140
	v_lshl_add_u64 v[146:147], v[142:143], 1, v[144:145]
	global_load_dwordx4 v[92:95], v[146:147], off offset:1536
	v_add_u32_e32 v140, 5, v0
	v_cmp_gt_u32_e32 vcc, s37, v140
	s_and_b64 vcc, s[40:41], vcc
	s_nop 1
	v_cndmask_b32_e32 v140, v141, v140, vcc
	v_mul_i32_i24_e32 v142, 0xd00, v140
	v_lshl_add_u64 v[146:147], v[142:143], 1, v[144:145]
	global_load_dwordx4 v[96:99], v[146:147], off offset:1536
	v_add_u32_e32 v140, 6, v0
	v_cmp_gt_u32_e32 vcc, s37, v140
	s_and_b64 vcc, s[40:41], vcc
	s_nop 1
	v_cndmask_b32_e32 v140, v141, v140, vcc
	v_mul_i32_i24_e32 v142, 0xd00, v140
	v_lshl_add_u64 v[146:147], v[142:143], 1, v[144:145]
	global_load_dwordx4 v[100:103], v[146:147], off offset:1536
	v_add_u32_e32 v140, 7, v0
	v_cmp_gt_u32_e32 vcc, s37, v140
	s_and_b64 vcc, s[40:41], vcc
	s_nop 1
	v_cndmask_b32_e32 v140, v141, v140, vcc
	v_mul_i32_i24_e32 v142, 0xd00, v140
	v_lshl_add_u64 v[146:147], v[142:143], 1, v[144:145]
	global_load_dwordx4 v[104:107], v[146:147], off offset:1536
	v_add_u32_e32 v140, 8, v0
	v_cndmask_b32_e64 v140, v141, v140, s[42:43]
	v_mul_i32_i24_e32 v142, 0xd00, v140
	v_lshl_add_u64 v[146:147], v[142:143], 1, v[144:145]
	global_load_dwordx4 v[108:111], v[146:147], off offset:1536
	v_add_u32_e32 v140, 9, v0
	v_cndmask_b32_e64 v140, v141, v140, s[42:43]
	v_mul_i32_i24_e32 v142, 0xd00, v140
	v_lshl_add_u64 v[146:147], v[142:143], 1, v[144:145]
	global_load_dwordx4 v[112:115], v[146:147], off offset:1536
	v_add_u32_e32 v140, 10, v0
	v_cndmask_b32_e64 v140, v141, v140, s[42:43]
	v_mul_i32_i24_e32 v142, 0xd00, v140
	v_lshl_add_u64 v[146:147], v[142:143], 1, v[144:145]
	global_load_dwordx4 v[116:119], v[146:147], off offset:1536
	v_add_u32_e32 v140, 11, v0
	v_cndmask_b32_e64 v140, v141, v140, s[42:43]
	v_mul_i32_i24_e32 v142, 0xd00, v140
	v_lshl_add_u64 v[146:147], v[142:143], 1, v[144:145]
	global_load_dwordx4 v[120:123], v[146:147], off offset:1536
	v_add_u32_e32 v140, 12, v0
	v_cndmask_b32_e64 v140, v141, v140, s[42:43]
	v_mul_i32_i24_e32 v142, 0xd00, v140
	v_lshl_add_u64 v[146:147], v[142:143], 1, v[144:145]
	global_load_dwordx4 v[124:127], v[146:147], off offset:1536
	v_add_u32_e32 v140, 13, v0
	v_cndmask_b32_e64 v140, v141, v140, s[42:43]
	v_mul_i32_i24_e32 v142, 0xd00, v140
	v_lshl_add_u64 v[146:147], v[142:143], 1, v[144:145]
	global_load_dwordx4 v[128:131], v[146:147], off offset:1536
	v_add_u32_e32 v140, 14, v0
	v_cndmask_b32_e64 v140, v141, v140, s[42:43]
	v_mul_i32_i24_e32 v142, 0xd00, v140
	v_lshl_add_u64 v[146:147], v[142:143], 1, v[144:145]
	global_load_dwordx4 v[132:135], v[146:147], off offset:1536
	v_add_u32_e32 v140, 15, v0
	v_cndmask_b32_e64 v140, v141, v140, s[42:43]
	v_mul_i32_i24_e32 v142, 0xd00, v140
	v_lshl_add_u64 v[146:147], v[142:143], 1, v[144:145]
	global_load_dwordx4 v[136:139], v[146:147], off offset:1536
	s_waitcnt vmcnt(0)
	v_cmp_gt_u32_e32 vcc, s37, v0
	v_mov_b32_e32 v1, s20
	s_and_b32 s19, s18, 0xffffe000
	v_mad_i64_i32 v[16:17], s[18:19], s19, v207, v[170:171]
	v_mov_b32_e32 v2, v76
	v_mov_b32_e32 v3, v77
	v_mov_b32_e32 v4, v78
	v_mov_b32_e32 v5, v79
	v_or_b32_e32 v38, s1, v200
	v_add_u32_e32 v39, s1, v201
	s_mov_b32 s18, -4
	s_waitcnt vmcnt(0)
	v_cndmask_b32_e32 v8, 0, v2, vcc
	v_add_u32_e32 v2, 1, v0
	v_cndmask_b32_e32 v12, 0, v5, vcc
	v_cndmask_b32_e32 v6, 0, v4, vcc
	v_cndmask_b32_e32 v7, 0, v3, vcc
	v_cmp_gt_u32_e32 vcc, s37, v2
	s_nop 1
	v_mov_b32_e32 v2, v80
	v_mov_b32_e32 v3, v81
	v_mov_b32_e32 v4, v82
	v_mov_b32_e32 v5, v83
	s_waitcnt vmcnt(0)
	v_cndmask_b32_e32 v10, 0, v2, vcc
	v_add_u32_e32 v2, 2, v0
	v_cndmask_b32_e32 v13, 0, v5, vcc
	v_cndmask_b32_e32 v14, 0, v4, vcc
	v_cndmask_b32_e32 v9, 0, v3, vcc
	v_cmp_gt_u32_e32 vcc, s37, v2
	s_and_b64 vcc, s[38:39], vcc
	s_nop 0
	v_mov_b32_e32 v2, v84
	v_mov_b32_e32 v3, v85
	v_mov_b32_e32 v4, v86
	v_mov_b32_e32 v5, v87
	s_waitcnt vmcnt(0)
	v_cndmask_b32_e32 v11, 0, v2, vcc
	v_add_u32_e32 v2, 3, v0
	v_cndmask_b32_e32 v15, 0, v5, vcc
	v_cndmask_b32_e32 v18, 0, v4, vcc
	v_cndmask_b32_e32 v19, 0, v3, vcc
	v_cmp_gt_u32_e32 vcc, s37, v2
	s_and_b64 vcc, s[38:39], vcc
	s_nop 0
	v_mov_b32_e32 v2, v88
	v_mov_b32_e32 v3, v89
	v_mov_b32_e32 v4, v90
	v_mov_b32_e32 v5, v91
	s_waitcnt vmcnt(0)
	v_cndmask_b32_e32 v23, 0, v2, vcc
	v_add_u32_e32 v2, 4, v0
	v_cndmask_b32_e32 v20, 0, v5, vcc
	v_cndmask_b32_e32 v21, 0, v4, vcc
	v_cndmask_b32_e32 v22, 0, v3, vcc
	v_cmp_gt_u32_e32 vcc, s37, v2
	s_and_b64 vcc, s[40:41], vcc
	s_nop 0
	v_mov_b32_e32 v2, v92
	v_mov_b32_e32 v3, v93
	v_mov_b32_e32 v4, v94
	v_mov_b32_e32 v5, v95
	s_waitcnt vmcnt(0)
	v_cndmask_b32_e32 v26, 0, v3, vcc
	v_cndmask_b32_e32 v27, 0, v2, vcc
	v_lshlrev_b32_e32 v2, 16, v8
	v_and_b32_e32 v3, 0xffff0000, v8
	v_cndmask_b32_e32 v24, 0, v5, vcc
	v_cndmask_b32_e32 v25, 0, v4, vcc
	v_pk_add_f32 v[2:3], v[2:3], 0 op_sel_hi:[1,0]
	v_lshlrev_b32_e32 v4, 16, v10
	v_and_b32_e32 v5, 0xffff0000, v10
	v_pk_add_f32 v[2:3], v[2:3], v[4:5]
	v_lshlrev_b32_e32 v4, 16, v11
	v_and_b32_e32 v5, 0xffff0000, v11
	v_pk_add_f32 v[2:3], v[2:3], v[4:5]
	v_lshlrev_b32_e32 v4, 16, v23
	v_and_b32_e32 v5, 0xffff0000, v23
	v_pk_add_f32 v[2:3], v[2:3], v[4:5]
	v_lshlrev_b32_e32 v4, 16, v27
	v_and_b32_e32 v5, 0xffff0000, v27
	v_pk_add_f32 v[10:11], v[2:3], v[4:5]
	v_lshlrev_b32_e32 v2, 16, v7
	v_and_b32_e32 v3, 0xffff0000, v7
	v_pk_add_f32 v[2:3], v[2:3], 0 op_sel_hi:[1,0]
	v_lshlrev_b32_e32 v4, 16, v9
	v_and_b32_e32 v5, 0xffff0000, v9
	v_pk_add_f32 v[2:3], v[2:3], v[4:5]
	v_lshlrev_b32_e32 v4, 16, v19
	v_and_b32_e32 v5, 0xffff0000, v19
	v_pk_add_f32 v[2:3], v[2:3], v[4:5]
	v_lshlrev_b32_e32 v4, 16, v22
	v_and_b32_e32 v5, 0xffff0000, v22
	v_pk_add_f32 v[2:3], v[2:3], v[4:5]
	v_lshlrev_b32_e32 v4, 16, v26
	v_and_b32_e32 v5, 0xffff0000, v26
	v_pk_add_f32 v[8:9], v[2:3], v[4:5]
	v_lshlrev_b32_e32 v2, 16, v6
	v_and_b32_e32 v3, 0xffff0000, v6
	v_pk_add_f32 v[2:3], v[2:3], 0 op_sel_hi:[1,0]
	v_lshlrev_b32_e32 v4, 16, v14
	v_and_b32_e32 v5, 0xffff0000, v14
	v_pk_add_f32 v[2:3], v[2:3], v[4:5]
	v_lshlrev_b32_e32 v4, 16, v18
	v_and_b32_e32 v5, 0xffff0000, v18
	v_pk_add_f32 v[2:3], v[2:3], v[4:5]
	v_lshlrev_b32_e32 v4, 16, v21
	v_and_b32_e32 v5, 0xffff0000, v21
	v_pk_add_f32 v[2:3], v[2:3], v[4:5]
	v_lshlrev_b32_e32 v4, 16, v25
	v_and_b32_e32 v5, 0xffff0000, v25
	v_pk_add_f32 v[6:7], v[2:3], v[4:5]
	v_lshlrev_b32_e32 v2, 16, v12
	v_and_b32_e32 v3, 0xffff0000, v12
	v_pk_add_f32 v[2:3], v[2:3], 0 op_sel_hi:[1,0]
	v_lshlrev_b32_e32 v4, 16, v13
	v_and_b32_e32 v5, 0xffff0000, v13
	v_pk_add_f32 v[2:3], v[2:3], v[4:5]
	v_lshlrev_b32_e32 v4, 16, v15
	v_and_b32_e32 v5, 0xffff0000, v15
	v_pk_add_f32 v[2:3], v[2:3], v[4:5]
	v_lshlrev_b32_e32 v4, 16, v20
	v_and_b32_e32 v5, 0xffff0000, v20
	v_pk_add_f32 v[2:3], v[2:3], v[4:5]
	v_lshlrev_b32_e32 v4, 16, v24
	v_and_b32_e32 v5, 0xffff0000, v24
	v_pk_add_f32 v[4:5], v[2:3], v[4:5]
	v_add_u32_e32 v2, 5, v0
	v_cmp_gt_u32_e32 vcc, s37, v2
	s_and_b64 vcc, s[40:41], vcc
	s_nop 0
	v_mov_b32_e32 v12, v96
	v_mov_b32_e32 v13, v97
	v_mov_b32_e32 v14, v98
	v_mov_b32_e32 v15, v99
	s_waitcnt vmcnt(0)
	v_cndmask_b32_e32 v2, 0, v15, vcc
	v_cndmask_b32_e32 v13, 0, v13, vcc
	v_cndmask_b32_e32 v12, 0, v12, vcc
	v_lshlrev_b32_e32 v20, 16, v12
	v_and_b32_e32 v21, 0xffff0000, v12
	v_lshlrev_b32_e32 v18, 16, v13
	v_and_b32_e32 v19, 0xffff0000, v13
	v_lshlrev_b32_e32 v12, 16, v2
	v_and_b32_e32 v13, 0xffff0000, v2
	v_add_u32_e32 v2, 6, v0
	v_cndmask_b32_e32 v3, 0, v14, vcc
	v_cmp_gt_u32_e32 vcc, s37, v2
	s_and_b64 vcc, s[40:41], vcc
	v_lshlrev_b32_e32 v14, 16, v3
	v_and_b32_e32 v15, 0xffff0000, v3
	v_mov_b32_e32 v22, v100
	v_mov_b32_e32 v23, v101
	v_mov_b32_e32 v24, v102
	v_mov_b32_e32 v25, v103
	v_pk_add_f32 v[8:9], v[8:9], v[18:19]
	v_pk_add_f32 v[6:7], v[6:7], v[14:15]
	v_pk_add_f32 v[4:5], v[4:5], v[12:13]
	s_waitcnt vmcnt(0)
	v_cndmask_b32_e32 v2, 0, v25, vcc
	v_cndmask_b32_e32 v23, 0, v23, vcc
	v_cndmask_b32_e32 v22, 0, v22, vcc
	v_lshlrev_b32_e32 v32, 16, v22
	v_and_b32_e32 v33, 0xffff0000, v22
	v_lshlrev_b32_e32 v28, 16, v23
	v_and_b32_e32 v29, 0xffff0000, v23
	v_lshlrev_b32_e32 v22, 16, v2
	v_and_b32_e32 v23, 0xffff0000, v2
	v_add_u32_e32 v2, 7, v0
	v_cndmask_b32_e32 v3, 0, v24, vcc
	v_cmp_gt_u32_e32 vcc, s37, v2
	s_and_b64 vcc, s[40:41], vcc
	v_lshlrev_b32_e32 v24, 16, v3
	v_and_b32_e32 v25, 0xffff0000, v3
	v_mov_b32_e32 v34, v104
	v_mov_b32_e32 v35, v105
	v_mov_b32_e32 v36, v106
	v_mov_b32_e32 v37, v107
	v_pk_add_f32 v[8:9], v[8:9], v[28:29]
	v_pk_add_f32 v[6:7], v[6:7], v[24:25]
	v_pk_add_f32 v[4:5], v[4:5], v[22:23]
	s_waitcnt vmcnt(0)
	v_cndmask_b32_e32 v2, 0, v37, vcc
	v_cndmask_b32_e32 v26, 0, v35, vcc
	v_cndmask_b32_e32 v27, 0, v34, vcc
	v_cndmask_b32_e32 v3, 0, v36, vcc
	v_lshlrev_b32_e32 v36, 16, v27
	v_and_b32_e32 v37, 0xffff0000, v27
	v_lshlrev_b32_e32 v34, 16, v26
	v_and_b32_e32 v35, 0xffff0000, v26
	v_lshlrev_b32_e32 v26, 16, v2
	v_and_b32_e32 v27, 0xffff0000, v2
	v_add_u32_e32 v2, 8, v0
	v_cndmask_b32_e64 v2, v1, v2, s[42:43]
	v_lshlrev_b32_e32 v30, 16, v3
	v_and_b32_e32 v31, 0xffff0000, v3
	v_mov_b32_e32 v44, v108
	v_mov_b32_e32 v45, v109
	v_mov_b32_e32 v46, v110
	v_mov_b32_e32 v47, v111
	v_add_u32_e32 v2, 9, v0
	v_cndmask_b32_e64 v2, v1, v2, s[42:43]
	v_mov_b32_e32 v48, v112
	v_mov_b32_e32 v49, v113
	v_mov_b32_e32 v50, v114
	v_mov_b32_e32 v51, v115
	v_add_u32_e32 v2, 10, v0
	v_cndmask_b32_e64 v2, v1, v2, s[42:43]
	v_mov_b32_e32 v56, v116
	v_mov_b32_e32 v57, v117
	v_mov_b32_e32 v58, v118
	v_mov_b32_e32 v59, v119
	v_add_u32_e32 v2, 11, v0
	v_cndmask_b32_e64 v2, v1, v2, s[42:43]
	v_pk_add_f32 v[8:9], v[8:9], v[34:35]
	v_pk_add_f32 v[6:7], v[6:7], v[30:31]
	v_pk_add_f32 v[4:5], v[4:5], v[26:27]
	s_waitcnt vmcnt(2)
	v_cndmask_b32_e64 v40, 0, v47, s[42:43]
	v_cndmask_b32_e64 v42, 0, v46, s[42:43]
	v_cndmask_b32_e64 v46, 0, v45, s[42:43]
	v_cndmask_b32_e64 v53, 0, v44, s[42:43]
	v_lshlrev_b32_e32 v14, 16, v42
	s_waitcnt vmcnt(1)
	v_cndmask_b32_e64 v41, 0, v51, s[42:43]
	v_cndmask_b32_e64 v62, 0, v48, s[42:43]
	v_cndmask_b32_e64 v44, 0, v50, s[42:43]
	v_cndmask_b32_e64 v50, 0, v49, s[42:43]
	v_and_b32_e32 v15, 0xffff0000, v42
	s_waitcnt vmcnt(0)
	v_cndmask_b32_e64 v43, 0, v59, s[42:43]
	v_cndmask_b32_e64 v47, 0, v58, s[42:43]
	v_cndmask_b32_e64 v54, 0, v57, s[42:43]
	v_cndmask_b32_e64 v63, 0, v56, s[42:43]
	v_mov_b32_e32 v56, v120
	v_mov_b32_e32 v57, v121
	v_mov_b32_e32 v58, v122
	v_mov_b32_e32 v59, v123
	v_mov_b32_e32 v143, 0
	v_lshl_add_u64 v[144:145], s[16:17], 0, v[154:155]
	v_add_co_u32_e32 v144, vcc, 0xa400000, v144
	s_nop 1
	v_addc_co_u32_e32 v145, vcc, 0, v145, vcc
	s_add_i32 s21, s1, s18
	s_add_i32 s21, s21, 4
	v_mov_b32_e32 v141, s21
	global_load_dwordx4 v[76:79], v[144:145], off offset:1536
	v_add_u32_e32 v140, s18, v38
	v_add_u32_e32 v140, 4, v140
	v_cmp_gt_u32_e32 vcc, s37, v140
	s_nop 1
	v_cndmask_b32_e32 v140, v141, v140, vcc
	v_mul_lo_u32 v142, v140, s55
	v_lshl_add_u64 v[146:147], v[142:143], 1, v[16:17]
	global_load_dwordx4 v[80:83], v[146:147], off offset:1536
	v_add_u32_e32 v140, s18, v39
	v_add_u32_e32 v140, 4, v140
	v_cmp_gt_i32_e32 vcc, 0, v140
	s_nop 1
	v_cndmask_b32_e32 v140, v140, v141, vcc
	v_mul_lo_u32 v148, v140, s55
	v_ashrrev_i32_e32 v149, 31, v148
	v_lshl_add_u64 v[146:147], v[148:149], 1, v[16:17]
	global_load_dwordx4 v[84:87], v[146:147], off offset:1536
	s_add_i32 s21, s1, s18
	s_add_i32 s21, s21, 5
	v_mov_b32_e32 v141, s21
	v_add_co_u32_e32 v146, vcc, 0x1a00, v144
	s_nop 1
	v_addc_co_u32_e32 v147, vcc, 0, v145, vcc
	global_load_dwordx4 v[88:91], v[146:147], off offset:1536
	v_add_u32_e32 v140, s18, v38
	v_add_u32_e32 v140, 5, v140
	v_cmp_gt_u32_e32 vcc, s37, v140
	s_nop 1
	v_cndmask_b32_e32 v140, v141, v140, vcc
	v_mul_lo_u32 v142, v140, s55
	v_lshl_add_u64 v[146:147], v[142:143], 1, v[16:17]
	global_load_dwordx4 v[92:95], v[146:147], off offset:1536
	v_add_u32_e32 v140, s18, v39
	v_add_u32_e32 v140, 5, v140
	v_cmp_gt_i32_e32 vcc, 0, v140
	s_nop 1
	v_cndmask_b32_e32 v140, v140, v141, vcc
	v_mul_lo_u32 v148, v140, s55
	v_ashrrev_i32_e32 v149, 31, v148
	v_lshl_add_u64 v[146:147], v[148:149], 1, v[16:17]
	global_load_dwordx4 v[96:99], v[146:147], off offset:1536
	s_add_i32 s21, s1, s18
	s_add_i32 s21, s21, 6
	v_mov_b32_e32 v141, s21
	v_add_co_u32_e32 v146, vcc, 0x3400, v144
	s_nop 1
	v_addc_co_u32_e32 v147, vcc, 0, v145, vcc
	global_load_dwordx4 v[100:103], v[146:147], off offset:1536
	v_add_u32_e32 v140, s18, v38
	v_add_u32_e32 v140, 6, v140
	v_cmp_gt_u32_e32 vcc, s37, v140
	s_nop 1
	v_cndmask_b32_e32 v140, v141, v140, vcc
	v_mul_lo_u32 v142, v140, s55
	v_lshl_add_u64 v[146:147], v[142:143], 1, v[16:17]
	global_load_dwordx4 v[104:107], v[146:147], off offset:1536
	v_add_u32_e32 v140, s18, v39
	v_add_u32_e32 v140, 6, v140
	v_cmp_gt_i32_e32 vcc, 0, v140
	s_nop 1
	v_cndmask_b32_e32 v140, v140, v141, vcc
	v_mul_lo_u32 v148, v140, s55
	v_ashrrev_i32_e32 v149, 31, v148
	v_lshl_add_u64 v[146:147], v[148:149], 1, v[16:17]
	global_load_dwordx4 v[108:111], v[146:147], off offset:1536
	s_add_i32 s21, s1, s18
	s_add_i32 s21, s21, 7
	v_mov_b32_e32 v141, s21
	v_add_co_u32_e32 v146, vcc, 0x4e00, v144
	s_nop 1
	v_addc_co_u32_e32 v147, vcc, 0, v145, vcc
	global_load_dwordx4 v[112:115], v[146:147], off offset:1536
	v_add_u32_e32 v140, s18, v38
	v_add_u32_e32 v140, 7, v140
	v_cmp_gt_u32_e32 vcc, s37, v140
	s_nop 1
	v_cndmask_b32_e32 v140, v141, v140, vcc
	v_mul_lo_u32 v142, v140, s55
	v_lshl_add_u64 v[146:147], v[142:143], 1, v[16:17]
	global_load_dwordx4 v[116:119], v[146:147], off offset:1536
	v_add_u32_e32 v140, s18, v39
	v_add_u32_e32 v140, 7, v140
	v_cmp_gt_i32_e32 vcc, 0, v140
	s_nop 1
	v_cndmask_b32_e32 v140, v140, v141, vcc
	v_mul_lo_u32 v148, v140, s55
	v_ashrrev_i32_e32 v149, 31, v148
	v_lshl_add_u64 v[146:147], v[148:149], 1, v[16:17]
	global_load_dwordx4 v[120:123], v[146:147], off offset:1536
	v_add_u32_e32 v2, 12, v0
	v_cndmask_b32_e64 v2, v1, v2, s[42:43]
	v_lshlrev_b32_e32 v12, 16, v40
	v_and_b32_e32 v13, 0xffff0000, v40
	v_pk_add_f32 v[6:7], v[6:7], v[14:15]
	v_lshlrev_b32_e32 v14, 16, v44
	v_and_b32_e32 v15, 0xffff0000, v44
	v_pk_add_f32 v[4:5], v[4:5], v[12:13]
	v_lshlrev_b32_e32 v12, 16, v41
	v_and_b32_e32 v13, 0xffff0000, v41
	v_pk_add_f32 v[6:7], v[6:7], v[14:15]
	v_lshlrev_b32_e32 v14, 16, v47
	v_and_b32_e32 v15, 0xffff0000, v47
	v_pk_add_f32 v[4:5], v[4:5], v[12:13]
	v_lshlrev_b32_e32 v12, 16, v43
	v_and_b32_e32 v13, 0xffff0000, v43
	v_pk_add_f32 v[6:7], v[6:7], v[14:15]
	v_pk_add_f32 v[4:5], v[4:5], v[12:13]
	v_cndmask_b32_e64 v45, 0, v59, s[42:43]
	v_cndmask_b32_e64 v51, 0, v58, s[42:43]
	v_cndmask_b32_e64 v64, 0, v57, s[42:43]
	v_cndmask_b32_e64 v65, 0, v56, s[42:43]
	v_mov_b32_e32 v56, v124
	v_mov_b32_e32 v57, v125
	v_mov_b32_e32 v58, v126
	v_mov_b32_e32 v59, v127
	v_add_u32_e32 v2, 13, v0
	v_cndmask_b32_e64 v2, v1, v2, s[42:43]
	v_lshlrev_b32_e32 v14, 16, v51
	v_and_b32_e32 v15, 0xffff0000, v51
	v_lshlrev_b32_e32 v12, 16, v45
	v_and_b32_e32 v13, 0xffff0000, v45
	v_pk_add_f32 v[6:7], v[6:7], v[14:15]
	v_pk_add_f32 v[4:5], v[4:5], v[12:13]
	v_cndmask_b32_e64 v48, 0, v59, s[42:43]
	v_cndmask_b32_e64 v55, 0, v58, s[42:43]
	v_mov_b32_e32 v58, v128
	v_mov_b32_e32 v59, v129
	v_mov_b32_e32 v60, v130
	v_mov_b32_e32 v61, v131
	v_add_u32_e32 v2, 14, v0
	v_cndmask_b32_e64 v2, v1, v2, s[42:43]
	v_add_u32_e32 v0, 15, v0
	v_cndmask_b32_e64 v0, v1, v0, s[42:43]
	v_mul_i32_i24_e32 v152, 0xd00, v0
	v_cndmask_b32_e64 v66, 0, v56, s[42:43]
	v_cndmask_b32_e64 v57, 0, v57, s[42:43]
	v_lshlrev_b32_e32 v14, 16, v55
	v_and_b32_e32 v15, 0xffff0000, v55
	v_lshlrev_b32_e32 v12, 16, v48
	v_and_b32_e32 v13, 0xffff0000, v48
	v_pk_add_f32 v[6:7], v[6:7], v[14:15]
	v_pk_add_f32 v[4:5], v[4:5], v[12:13]
	v_cndmask_b32_e64 v49, 0, v61, s[42:43]
	v_cndmask_b32_e64 v56, 0, v60, s[42:43]
	v_cndmask_b32_e64 v67, 0, v59, s[42:43]
	v_cndmask_b32_e64 v68, 0, v58, s[42:43]
	v_mov_b32_e32 v58, v132
	v_mov_b32_e32 v59, v133
	v_mov_b32_e32 v60, v134
	v_mov_b32_e32 v61, v135
	v_lshlrev_b32_e32 v14, 16, v56
	v_mov_b32_e32 v0, v136
	v_mov_b32_e32 v1, v137
	v_mov_b32_e32 v2, v138
	v_mov_b32_e32 v3, v139
	v_and_b32_e32 v15, 0xffff0000, v56
	v_lshlrev_b32_e32 v12, 16, v49
	v_and_b32_e32 v13, 0xffff0000, v49
	v_pk_add_f32 v[6:7], v[6:7], v[14:15]
	v_pk_add_f32 v[4:5], v[4:5], v[12:13]
	v_cndmask_b32_e64 v52, 0, v61, s[42:43]
	v_cndmask_b32_e64 v60, 0, v60, s[42:43]
	v_cndmask_b32_e64 v70, 0, v1, s[42:43]
	v_cndmask_b32_e64 v71, 0, v0, s[42:43]
	v_pk_add_f32 v[0:1], v[10:11], v[20:21]
	v_cndmask_b32_e64 v61, 0, v3, s[42:43]
	v_pk_add_f32 v[0:1], v[0:1], v[32:33]
	v_cndmask_b32_e64 v69, 0, v2, s[42:43]
	v_pk_add_f32 v[0:1], v[0:1], v[36:37]
	v_lshlrev_b32_e32 v2, 16, v53
	v_and_b32_e32 v3, 0xffff0000, v53
	v_lshlrev_b32_e32 v10, 16, v46
	v_and_b32_e32 v11, 0xffff0000, v46
	v_pk_add_f32 v[0:1], v[0:1], v[2:3]
	v_lshlrev_b32_e32 v2, 16, v62
	v_and_b32_e32 v3, 0xffff0000, v62
	v_pk_add_f32 v[8:9], v[8:9], v[10:11]
	v_lshlrev_b32_e32 v10, 16, v50
	v_and_b32_e32 v11, 0xffff0000, v50
	v_pk_add_f32 v[0:1], v[0:1], v[2:3]
	v_lshlrev_b32_e32 v2, 16, v63
	v_and_b32_e32 v3, 0xffff0000, v63
	v_pk_add_f32 v[8:9], v[8:9], v[10:11]
	v_lshlrev_b32_e32 v10, 16, v54
	v_and_b32_e32 v11, 0xffff0000, v54
	v_pk_add_f32 v[0:1], v[0:1], v[2:3]
	v_lshlrev_b32_e32 v2, 16, v65
	v_and_b32_e32 v3, 0xffff0000, v65
	v_pk_add_f32 v[8:9], v[8:9], v[10:11]
	v_lshlrev_b32_e32 v10, 16, v64
	v_and_b32_e32 v11, 0xffff0000, v64
	v_pk_add_f32 v[0:1], v[0:1], v[2:3]
	v_lshlrev_b32_e32 v2, 16, v66
	v_and_b32_e32 v3, 0xffff0000, v66
	v_pk_add_f32 v[8:9], v[8:9], v[10:11]
	v_lshlrev_b32_e32 v10, 16, v57
	v_and_b32_e32 v11, 0xffff0000, v57
	v_cndmask_b32_e64 v59, 0, v59, s[42:43]
	v_cndmask_b32_e64 v58, 0, v58, s[42:43]
	v_pk_add_f32 v[0:1], v[0:1], v[2:3]
	v_lshlrev_b32_e32 v2, 16, v68
	v_and_b32_e32 v3, 0xffff0000, v68
	v_pk_add_f32 v[8:9], v[8:9], v[10:11]
	v_lshlrev_b32_e32 v10, 16, v67
	v_and_b32_e32 v11, 0xffff0000, v67
	v_pk_add_f32 v[0:1], v[0:1], v[2:3]
	v_lshlrev_b32_e32 v2, 16, v58
	v_and_b32_e32 v3, 0xffff0000, v58
	v_pk_add_f32 v[8:9], v[8:9], v[10:11]
	v_lshlrev_b32_e32 v10, 16, v59
	v_and_b32_e32 v11, 0xffff0000, v59
	v_lshlrev_b32_e32 v14, 16, v60
	v_and_b32_e32 v15, 0xffff0000, v60
	v_lshlrev_b32_e32 v12, 16, v52
	v_and_b32_e32 v13, 0xffff0000, v52
	v_pk_add_f32 v[0:1], v[0:1], v[2:3]
	v_lshlrev_b32_e32 v2, 16, v71
	v_and_b32_e32 v3, 0xffff0000, v71
	v_pk_add_f32 v[8:9], v[8:9], v[10:11]
	v_lshlrev_b32_e32 v10, 16, v70
	v_and_b32_e32 v11, 0xffff0000, v70
	v_pk_add_f32 v[6:7], v[6:7], v[14:15]
	v_lshlrev_b32_e32 v14, 16, v69
	v_and_b32_e32 v15, 0xffff0000, v69
	v_pk_add_f32 v[4:5], v[4:5], v[12:13]
	v_lshlrev_b32_e32 v12, 16, v61
	v_and_b32_e32 v13, 0xffff0000, v61
	v_pk_add_f32 v[18:19], v[0:1], v[2:3]
	v_pk_add_f32 v[22:23], v[8:9], v[10:11]
	v_pk_add_f32 v[20:21], v[6:7], v[14:15]
	v_pk_add_f32 v[24:25], v[4:5], v[12:13]
.LBB0_613:
	s_waitcnt vmcnt(0)
	s_add_i32 s19, s1, s18
	v_add_u32_e32 v26, s18, v38
	s_add_i32 s20, s19, 4
	v_add_u32_e32 v72, 4, v26
	v_cmp_gt_u32_e32 vcc, s37, v72
	v_mov_b32_e32 v12, v76
	v_mov_b32_e32 v13, v77
	v_mov_b32_e32 v14, v78
	v_mov_b32_e32 v15, v79
	v_mov_b32_e32 v0, v80
	v_mov_b32_e32 v1, v81
	v_mov_b32_e32 v2, v82
	v_mov_b32_e32 v3, v83
	v_add_u32_e32 v41, s18, v39
	v_add_u32_e32 v73, 4, v41
	s_mov_b32 s21, 0xa402000
	s_add_i32 s20, s19, 5
	v_add_u32_e32 v57, 5, v26
	v_add_u32_e32 v58, 5, v41
	s_add_i32 s20, s19, 6
	v_add_u32_e32 v62, 6, v26
	v_add_u32_e32 v63, 6, v41
	s_mov_b32 s20, 0xa405000
	s_add_i32 s19, s19, 7
	v_add_u32_e32 v65, 7, v26
	v_mov_b32_e32 v26, s19
	v_add_u32_e32 v66, 7, v41
	s_mov_b32 s19, 0x1d400000
	s_add_i32 s18, s18, 4
	s_waitcnt vmcnt(0)
	v_cndmask_b32_e32 v27, 0, v3, vcc
	v_cndmask_b32_e32 v32, 0, v2, vcc
	v_cndmask_b32_e32 v42, 0, v1, vcc
	v_cndmask_b32_e32 v47, 0, v0, vcc
	v_cmp_gt_i32_e32 vcc, 0, v73
	s_nop 1
	v_mov_b32_e32 v0, v84
	v_mov_b32_e32 v1, v85
	v_mov_b32_e32 v2, v86
	v_mov_b32_e32 v3, v87
	s_waitcnt vmcnt(0)
	v_cndmask_b32_e64 v30, v3, 0, vcc
	v_cndmask_b32_e64 v34, v2, 0, vcc
	v_cndmask_b32_e64 v45, v1, 0, vcc
	v_cndmask_b32_e64 v48, v0, 0, vcc
	s_mov_b32 s21, 0xa403000
	s_nop 0
	v_cmp_gt_u32_e32 vcc, s37, v57
	v_mov_b32_e32 v0, v88
	v_mov_b32_e32 v1, v89
	v_mov_b32_e32 v2, v90
	v_mov_b32_e32 v3, v91
	s_nop 0
	v_mov_b32_e32 v4, v92
	v_mov_b32_e32 v5, v93
	v_mov_b32_e32 v6, v94
	v_mov_b32_e32 v7, v95
	s_waitcnt vmcnt(0)
	v_cndmask_b32_e32 v31, 0, v7, vcc
	v_cndmask_b32_e32 v37, 0, v6, vcc
	v_cndmask_b32_e32 v49, 0, v5, vcc
	v_cndmask_b32_e32 v55, 0, v4, vcc
	v_cmp_gt_i32_e32 vcc, 0, v58
	s_nop 1
	v_mov_b32_e32 v4, v96
	v_mov_b32_e32 v5, v97
	v_mov_b32_e32 v6, v98
	v_mov_b32_e32 v7, v99
	s_waitcnt vmcnt(0)
	v_cndmask_b32_e64 v33, v7, 0, vcc
	v_cndmask_b32_e64 v40, v6, 0, vcc
	v_cndmask_b32_e64 v51, v5, 0, vcc
	v_cndmask_b32_e64 v56, v4, 0, vcc
	s_nop 1
	v_cmp_gt_u32_e32 vcc, s37, v62
	v_mov_b32_e32 v4, v100
	v_mov_b32_e32 v5, v101
	v_mov_b32_e32 v6, v102
	v_mov_b32_e32 v7, v103
	s_nop 0
	v_mov_b32_e32 v8, v104
	v_mov_b32_e32 v9, v105
	v_mov_b32_e32 v10, v106
	v_mov_b32_e32 v11, v107
	s_waitcnt vmcnt(0)
	v_cndmask_b32_e32 v35, 0, v11, vcc
	v_cndmask_b32_e32 v44, 0, v10, vcc
	v_cndmask_b32_e32 v53, 0, v9, vcc
	v_cndmask_b32_e32 v61, 0, v8, vcc
	v_cmp_gt_i32_e32 vcc, 0, v63
	s_nop 1
	v_mov_b32_e32 v8, v108
	v_mov_b32_e32 v9, v109
	v_mov_b32_e32 v10, v110
	v_mov_b32_e32 v11, v111
	s_waitcnt vmcnt(0)
	v_cndmask_b32_e64 v36, v11, 0, vcc
	v_cndmask_b32_e64 v46, v10, 0, vcc
	v_cndmask_b32_e64 v54, v9, 0, vcc
	v_cndmask_b32_e64 v64, v8, 0, vcc
	s_nop 1
	v_cmp_gt_u32_e32 vcc, s37, v65
	v_mov_b32_e32 v8, v112
	v_mov_b32_e32 v9, v113
	v_mov_b32_e32 v10, v114
	v_mov_b32_e32 v11, v115
	s_nop 0
	v_cndmask_b32_e32 v28, v26, v65, vcc
	v_mul_lo_u32 v152, v28, s55
	v_mov_b32_e32 v68, v116
	v_mov_b32_e32 v69, v117
	v_mov_b32_e32 v70, v118
	v_mov_b32_e32 v71, v119
	s_waitcnt vmcnt(0)
	v_cndmask_b32_e32 v41, 0, v71, vcc
	v_cndmask_b32_e32 v50, 0, v70, vcc
	v_cndmask_b32_e32 v59, 0, v69, vcc
	v_cndmask_b32_e32 v67, 0, v68, vcc
	v_cmp_gt_i32_e32 vcc, 0, v66
	s_nop 1
	v_mov_b32_e32 v68, v120
	v_mov_b32_e32 v69, v121
	v_mov_b32_e32 v70, v122
	v_mov_b32_e32 v71, v123
	v_max_i32_e32 v26, 0, v73
	v_min_u32_e32 v28, 0x2000, v72
	v_sub_u32_e32 v26, v28, v26
	v_cvt_f32_i32_e32 v26, v26
	v_mov_b32_e32 v72, v20
	v_mov_b32_e32 v73, v24
	v_div_scale_f32 v28, s[20:21], v26, v26, 1.0
	v_rcp_f32_e32 v29, v28
	s_waitcnt vmcnt(0)
	v_cndmask_b32_e64 v60, v69, 0, vcc
	v_fma_f32 v69, -v28, v29, 1.0
	v_cndmask_b32_e64 v43, v71, 0, vcc
	v_cndmask_b32_e64 v52, v70, 0, vcc
	v_cndmask_b32_e64 v68, v68, 0, vcc
	s_cmp_lt_u32 s18, 12
	s_cbranch_scc0 .Lmy_pool_nopf
	v_mov_b32_e32 v143, 0
	v_lshl_add_u64 v[144:145], s[16:17], 0, v[154:155]
	v_add_co_u32_e32 v144, vcc, 0xa406800, v144
	s_nop 1
	v_addc_co_u32_e32 v145, vcc, 0, v145, vcc
	s_add_i32 s21, s1, s18
	s_add_i32 s21, s21, 4
	v_mov_b32_e32 v141, s21
	global_load_dwordx4 v[76:79], v[144:145], off offset:1536
	v_add_u32_e32 v140, s18, v38
	v_add_u32_e32 v140, 4, v140
	v_cmp_gt_u32_e32 vcc, s37, v140
	s_nop 1
	v_cndmask_b32_e32 v140, v141, v140, vcc
	v_mul_lo_u32 v142, v140, s55
	v_lshl_add_u64 v[146:147], v[142:143], 1, v[16:17]
	global_load_dwordx4 v[80:83], v[146:147], off offset:1536
	v_add_u32_e32 v140, s18, v39
	v_add_u32_e32 v140, 4, v140
	v_cmp_gt_i32_e32 vcc, 0, v140
	s_nop 1
	v_cndmask_b32_e32 v140, v140, v141, vcc
	v_mul_lo_u32 v148, v140, s55
	v_ashrrev_i32_e32 v149, 31, v148
	v_lshl_add_u64 v[146:147], v[148:149], 1, v[16:17]
	global_load_dwordx4 v[84:87], v[146:147], off offset:1536
	s_add_i32 s21, s1, s18
	s_add_i32 s21, s21, 5
	v_mov_b32_e32 v141, s21
	v_add_co_u32_e32 v146, vcc, 0x1a00, v144
	s_nop 1
	v_addc_co_u32_e32 v147, vcc, 0, v145, vcc
	global_load_dwordx4 v[88:91], v[146:147], off offset:1536
	v_add_u32_e32 v140, s18, v38
	v_add_u32_e32 v140, 5, v140
	v_cmp_gt_u32_e32 vcc, s37, v140
	s_nop 1
	v_cndmask_b32_e32 v140, v141, v140, vcc
	v_mul_lo_u32 v142, v140, s55
	v_lshl_add_u64 v[146:147], v[142:143], 1, v[16:17]
	global_load_dwordx4 v[92:95], v[146:147], off offset:1536
	v_add_u32_e32 v140, s18, v39
	v_add_u32_e32 v140, 5, v140
	v_cmp_gt_i32_e32 vcc, 0, v140
	s_nop 1
	v_cndmask_b32_e32 v140, v140, v141, vcc
	v_mul_lo_u32 v148, v140, s55
	v_ashrrev_i32_e32 v149, 31, v148
	v_lshl_add_u64 v[146:147], v[148:149], 1, v[16:17]
	global_load_dwordx4 v[96:99], v[146:147], off offset:1536
	s_add_i32 s21, s1, s18
	s_add_i32 s21, s21, 6
	v_mov_b32_e32 v141, s21
	v_add_co_u32_e32 v146, vcc, 0x3400, v144
	s_nop 1
	v_addc_co_u32_e32 v147, vcc, 0, v145, vcc
	global_load_dwordx4 v[100:103], v[146:147], off offset:1536
	v_add_u32_e32 v140, s18, v38
	v_add_u32_e32 v140, 6, v140
	v_cmp_gt_u32_e32 vcc, s37, v140
	s_nop 1
	v_cndmask_b32_e32 v140, v141, v140, vcc
	v_mul_lo_u32 v142, v140, s55
	v_lshl_add_u64 v[146:147], v[142:143], 1, v[16:17]
	global_load_dwordx4 v[104:107], v[146:147], off offset:1536
	v_add_u32_e32 v140, s18, v39
	v_add_u32_e32 v140, 6, v140
	v_cmp_gt_i32_e32 vcc, 0, v140
	s_nop 1
	v_cndmask_b32_e32 v140, v140, v141, vcc
	v_mul_lo_u32 v148, v140, s55
	v_ashrrev_i32_e32 v149, 31, v148
	v_lshl_add_u64 v[146:147], v[148:149], 1, v[16:17]
	global_load_dwordx4 v[108:111], v[146:147], off offset:1536
	s_add_i32 s21, s1, s18
	s_add_i32 s21, s21, 7
	v_mov_b32_e32 v141, s21
	v_add_co_u32_e32 v146, vcc, 0x4e00, v144
	s_nop 1
	v_addc_co_u32_e32 v147, vcc, 0, v145, vcc
	global_load_dwordx4 v[112:115], v[146:147], off offset:1536
	v_add_u32_e32 v140, s18, v38
	v_add_u32_e32 v140, 7, v140
	v_cmp_gt_u32_e32 vcc, s37, v140
	s_nop 1
	v_cndmask_b32_e32 v140, v141, v140, vcc
	v_mul_lo_u32 v142, v140, s55
	v_lshl_add_u64 v[146:147], v[142:143], 1, v[16:17]
	global_load_dwordx4 v[116:119], v[146:147], off offset:1536
	v_add_u32_e32 v140, s18, v39
	v_add_u32_e32 v140, 7, v140
	v_cmp_gt_i32_e32 vcc, 0, v140
	s_nop 1
	v_cndmask_b32_e32 v140, v140, v141, vcc
	v_mul_lo_u32 v148, v140, s55
	v_ashrrev_i32_e32 v149, 31, v148
	v_lshl_add_u64 v[146:147], v[148:149], 1, v[16:17]
	global_load_dwordx4 v[120:123], v[146:147], off offset:1536
